# mixer priorities: mLSTM output items raised to 3, the 128 longest FoX items per queue to 2
# speedup vs baseline: 1.0029x; 1.0011x over previous
; #define LAS __attribute__((address_space(3)))
; template <bool OUT>
; __device__ __forceinline__ void mlstm_item(const bf16* u, bf16* y, float* scratch, const float* convw, const float* ib, const float* fbias, const float* normw, LAS unsigned char* wl, int bh, int c, int lane) {
;     const int b = bh / 6, h = bh % 6, r = lane & 31, hi = lane >> 5;
;     const bf16* ub = u + (size_t)b * S * NU;
;     LAS float* cw = (LAS float*)(wl + ML_CW); LAS float* eb = (LAS float*)(wl + ML_EB); LAS float* nl = (LAS float*)(wl + ML_NL); LAS float* nwl = (LAS float*)(wl + ML_NW);
;     for (int i = lane; i < 512; i += 64) { const int tap = i >> 7, ch = i & 127; cw[i] = convw[tap * 768 + (ch < 64 ? (64 * h + ch) : (384 + 64 * h + (ch - 64)))]; }
; __global__ void __launch_bounds__(512, 2) mega_fwd(Args a) {
;     ...
;                     if (isc) { const int ci = it - 522; __builtin_amdgcn_s_setprio(2); mlstm_item<true>(ub, yb, mscr, prm + 512, prm + 8, prm + 16, prm + 64, L + wave * ML_WSTRIDE, xcd + 8 * (ci >> 4), 15 - (ci & 15), lane); __builtin_amdgcn_s_setprio(0); }
.LBB0_780:
	s_setprio 3
	s_lshr_b32 s0, s3, 1
	s_and_b32 s0, s0, 0xfff8
	s_or_b32 s0, s0, s69
	s_and_b32 s1, s0, 0xff
	s_mulk_i32 s1, 0xab
	s_lshr_b32 s50, s1, 10
	s_mul_i32 s1, s50, 6
	s_sub_i32 s0, s0, s1
	s_and_b32 s33, s0, 0xff
	s_lshl_b32 s52, s33, 6
	s_add_i32 s51, s52, 0x140
	s_mov_b64 s[0:1], 0
	v_mov_b32_e32 v1, v220
	v_mov_b32_e32 v4, v202
